# prep step 2: row-side decay and beta scalars read from LDS once per unit instead of before each masked use (32 fewer serialized LDS round trips)
# baseline (speedup 1.0000x reference)
; #define PG8_LAS __attribute__((address_space(3)))
; #define MFMA16(a, b, c) __builtin_amdgcn_mfma_f32_16x16x32_bf16((a), (b), (c), 0, 0, 0)
; __device__ __forceinline__ bf16_t f2bf(float x) { return (bf16_t)(pk2(x, x) & 0xffffu); }
; __device__ __forceinline__ void phase_prep(const Args& a, PG8_LAS unsigned char* lds) {
;     ...
;         {
; #pragma unroll
;             for (int tj = 0; tj < 4; ++tj) {
;                 f32x4 ckk = {0.f, 0.f, 0.f, 0.f}, cqk = {0.f, 0.f, 0.f, 0.f};
; #pragma unroll
;                 for (int s = 0; s < 4; ++s) { const bf16x8 bk = (tj < 2) ? bkf[tj & 1][s] : *(const bf16x8*)(kbase + (size_t)(16 * tj + r) * 512 + 32 * s + 8 * q); ckk = MFMA16(ak[s], bk, ckk); cqk = MFMA16(aq[s], bk, cqk); }
;                 const int j = 16 * tj + r; const float Gj = sG[j]; const int jpos = (j & 32) + perm32s(j & 31);
;                 f32x4 lv;
; #pragma unroll
;                 for (int e = 0; e < 4; ++e) { const int i = 16 * lw + 4 * q + e; const float Gi = sG[i], bi = sB[i];
;                     const float dec = (i >= j) ? __expf(Gi - Gj) : 0.f;
;                     lv[e] = (i > j) ? ckk[e] * bi * dec : 0.f;
;                     aqkp[i * 64 + jpos] = f2bf((i >= j) ? cqk[e] * dec : 0.f); }
;                 *(PG8_LAS f32x4*)(sL + j * 64 + 16 * lw + 4 * q) = lv;
.Lpp_w1:
	ds_write_b128 v255, v[56:59]
	ds_write_b128 v255, v[48:51] offset:1024
	ds_write_b128 v255, v[40:43] offset:2048
	ds_write_b128 v255, v[32:35] offset:3072
	s_waitcnt lgkmcnt(0)
	s_barrier
	ds_read_b128 v[92:95], v254
	ds_read_b128 v[88:91], v254 offset:1024
	ds_read_b128 v[84:87], v254 offset:2048
	ds_read_b128 v[80:83], v254 offset:3072
	ds_read_b128 v[76:79], v254 offset:4096
	ds_read_b128 v[72:75], v254 offset:5120
	ds_read_b128 v[68:71], v254 offset:6144
	ds_read_b128 v[64:67], v254 offset:7168
	ds_read_b32 v107, v138
	ds_read_b32 v109, v138 offset:4
	ds_read_b32 v111, v138 offset:8
	ds_read_b32 v113, v138 offset:12
	ds_read_b32 v117, v138 offset:256
	ds_read_b32 v119, v138 offset:260
	ds_read_b32 v121, v138 offset:264
	ds_read_b32 v123, v138 offset:268
	s_waitcnt lgkmcnt(0)
	v_mfma_f32_16x16x32_bf16 v[230:233], v[56:59], v[92:95], 0
	v_mfma_f32_16x16x32_bf16 v[92:95], v[60:63], v[92:95], 0
	v_readlane_b32 s40, v252, 5
	v_readlane_b32 s41, v252, 6
	v_mfma_f32_16x16x32_bf16 v[230:233], v[48:51], v[88:91], v[230:233]
	v_mfma_f32_16x16x32_bf16 v[88:91], v[52:55], v[88:91], v[92:95]
	v_mfma_f32_16x16x32_bf16 v[92:95], v[40:43], v[84:87], v[230:233]
	v_mfma_f32_16x16x32_bf16 v[230:233], v[44:47], v[84:87], v[88:91]
	s_nop 5
	ds_read_b32 v90, v137
	v_mov_b32_e32 v89, v117
	v_mov_b32_e32 v88, 0
	v_mov_b32_e32 v91, 0
	v_mfma_f32_16x16x32_bf16 v[84:87], v[32:35], v[80:83], v[92:95]
	v_mfma_f32_16x16x32_bf16 v[80:83], v[36:39], v[80:83], v[230:233]
	s_and_saveexec_b64 s[26:27], s[40:41]
	s_cbranch_execz .LBB0_261
	v_mov_b32_e32 v91, v107
	s_waitcnt lgkmcnt(0)
	v_sub_f32_e32 v91, v91, v90
	v_mul_f32_e32 v91, 0x3fb8aa3b, v91
	v_exp_f32_e32 v91, v91
.LBB0_261:
	s_or_b64 exec, exec, s[26:27]
	s_nop 4
	v_mul_f32_e32 v80, v80, v91
	v_cndmask_b32_e64 v80, v80, 0, s[12:13]
	s_mul_hi_i32 s14, s18, 0x12000
	s_mul_i32 s18, s18, 0x12000
	v_cvt_pk_bf16_f32 v80, v80, v80
	v_mov_b32_e32 v92, v119
	s_add_u32 s18, s29, s18
	s_addc_u32 s19, s30, s14
	s_add_u32 s26, s18, 0x10000
	s_addc_u32 s27, s19, 0
	v_mov_b32_e32 v93, 0
	global_store_short v207, v80, s[26:27]
	s_mov_b64 vcc, exec
	v_readlane_b32 s40, v252, 11
	v_readlane_b32 s41, v252, 12
	s_and_b64 s[40:41], vcc, s[40:41]
	s_mov_b64 exec, s[40:41]
	s_cbranch_execz .LBB0_263
	v_mov_b32_e32 v80, v109
	s_waitcnt lgkmcnt(0)
	v_sub_f32_e32 v80, v80, v90
	v_mul_f32_e32 v80, 0x3fb8aa3b, v80
	v_exp_f32_e32 v93, v80
.LBB0_263:
	s_or_b64 exec, exec, vcc
	v_readlane_b32 s40, v252, 9
	v_mul_f32_e32 v80, v81, v93
	v_readlane_b32 s41, v252, 10
	s_nop 1
	v_cndmask_b32_e64 v80, v80, 0, s[40:41]
	v_cvt_pk_bf16_f32 v80, v80, v80
	v_mov_b32_e32 v81, v121
	global_store_short v208, v80, s[26:27]
	s_mov_b64 vcc, exec
	v_readlane_b32 s40, v252, 15
	v_readlane_b32 s41, v252, 16
	s_and_b64 s[40:41], vcc, s[40:41]
	s_mov_b64 exec, s[40:41]
	s_cbranch_execz .LBB0_265
	v_mov_b32_e32 v80, v111
	s_waitcnt lgkmcnt(0)
	v_sub_f32_e32 v80, v80, v90
	v_mul_f32_e32 v80, 0x3fb8aa3b, v80
	v_exp_f32_e32 v88, v80
.LBB0_265:
	s_or_b64 exec, exec, vcc
	v_readlane_b32 s40, v252, 13
	v_mul_f32_e32 v80, v82, v88
	v_readlane_b32 s41, v252, 14
	s_nop 1
	v_cndmask_b32_e64 v80, v80, 0, s[40:41]
	v_cvt_pk_bf16_f32 v94, v80, v80
	v_mov_b32_e32 v82, v123
	v_mov_b32_e32 v80, 0
	global_store_short v209, v94, s[26:27]
	v_mov_b32_e32 v94, 0
	s_mov_b64 vcc, exec
	v_readlane_b32 s40, v252, 21
	v_readlane_b32 s41, v252, 22
	s_and_b64 s[40:41], vcc, s[40:41]
	s_mov_b64 exec, s[40:41]
	s_cbranch_execz .LBB0_267
	v_mov_b32_e32 v94, v113
	s_waitcnt lgkmcnt(0)
	v_sub_f32_e32 v90, v94, v90
	v_mul_f32_e32 v90, 0x3fb8aa3b, v90
	v_exp_f32_e32 v94, v90
.LBB0_267:
	s_or_b64 exec, exec, vcc
	s_waitcnt lgkmcnt(3)
	v_mul_f32_e32 v84, v84, v89
	v_readlane_b32 s40, v252, 7
	v_mul_f32_e32 v84, v84, v91
	v_readlane_b32 s41, v252, 8
	s_waitcnt lgkmcnt(1)
	v_mul_f32_e32 v81, v86, v81
	v_mul_f32_e32 v81, v81, v88
	v_cndmask_b32_e64 v84, 0, v84, s[40:41]
	v_readlane_b32 s40, v252, 17
	v_readlane_b32 s41, v252, 18
	v_mul_f32_e32 v85, v85, v92
	v_mul_f32_e32 v85, v85, v93
	v_cndmask_b32_e64 v86, 0, v81, s[40:41]
	s_waitcnt lgkmcnt(0)
	v_mul_f32_e32 v81, v87, v82
	v_readlane_b32 s40, v252, 23
	v_mul_f32_e32 v81, v81, v94
	v_readlane_b32 s41, v252, 24
	v_cndmask_b32_e64 v85, v85, 0, s[12:13]
	s_nop 0
	v_cndmask_b32_e64 v87, 0, v81, s[40:41]
	v_readlane_b32 s40, v252, 19
	v_mul_f32_e32 v81, v83, v94
	v_readlane_b32 s41, v252, 20
	s_nop 1
	v_cndmask_b32_e64 v81, v81, 0, s[40:41]
	v_cvt_pk_bf16_f32 v81, v81, v81
	ds_write_b128 v211, v[84:87] offset:1024
	v_mfma_f32_16x16x32_bf16 v[82:85], v[56:59], v[76:79], 0
	global_store_short v210, v81, s[26:27]
	v_mfma_f32_16x16x32_bf16 v[76:79], v[60:63], v[76:79], 0
	v_mfma_f32_16x16x32_bf16 v[82:85], v[48:51], v[72:75], v[82:85]
	v_mfma_f32_16x16x32_bf16 v[72:75], v[52:55], v[72:75], v[76:79]
	v_mfma_f32_16x16x32_bf16 v[76:79], v[40:43], v[68:71], v[82:85]
	v_mfma_f32_16x16x32_bf16 v[72:75], v[44:47], v[68:71], v[72:75]
	v_mfma_f32_16x16x32_bf16 v[68:71], v[32:35], v[64:67], v[76:79]
	v_mfma_f32_16x16x32_bf16 v[64:67], v[36:39], v[64:67], v[72:75]
	s_nop 5
	ds_read_b32 v74, v137 offset:64
	v_mov_b32_e32 v73, v117
	s_mov_b64 vcc, exec
	v_readlane_b32 s40, v252, 25
	v_readlane_b32 s41, v252, 26
	s_and_b64 s[40:41], vcc, s[40:41]
	s_mov_b64 exec, s[40:41]
	s_cbranch_execz .LBB0_269
	v_mov_b32_e32 v72, v107
	s_waitcnt lgkmcnt(0)
	v_sub_f32_e32 v72, v72, v74
	v_mul_f32_e32 v72, 0x3fb8aa3b, v72
	v_exp_f32_e32 v80, v72
.LBB0_269:
	s_or_b64 exec, exec, vcc
	v_mul_f32_e32 v64, v64, v80
	v_cndmask_b32_e64 v64, v64, 0, s[36:37]
	v_cvt_pk_bf16_f32 v64, v64, v64
	v_mov_b32_e32 v75, v119
	v_mov_b32_e32 v76, 0
	v_mov_b32_e32 v77, 0
	global_store_short v212, v64, s[26:27]
	s_and_saveexec_b64 vcc, s[44:45]
	s_cbranch_execz .LBB0_271
	v_mov_b32_e32 v64, v109
	s_waitcnt lgkmcnt(0)
	v_sub_f32_e32 v64, v64, v74
	v_mul_f32_e32 v64, 0x3fb8aa3b, v64
	v_exp_f32_e32 v77, v64
; #define PG8_LAS __attribute__((address_space(3)))
; #define MFMA16(a, b, c) __builtin_amdgcn_mfma_f32_16x16x32_bf16((a), (b), (c), 0, 0, 0)
; __device__ __forceinline__ bf16_t f2bf(float x) { return (bf16_t)(pk2(x, x) & 0xffffu); }
; __device__ __forceinline__ void phase_prep(const Args& a, PG8_LAS unsigned char* lds) {
;     ...
;         {
; #pragma unroll
;             for (int tj = 0; tj < 4; ++tj) {
;                 f32x4 ckk = {0.f, 0.f, 0.f, 0.f}, cqk = {0.f, 0.f, 0.f, 0.f};
; #pragma unroll
;                 for (int s = 0; s < 4; ++s) { const bf16x8 bk = (tj < 2) ? bkf[tj & 1][s] : *(const bf16x8*)(kbase + (size_t)(16 * tj + r) * 512 + 32 * s + 8 * q); ckk = MFMA16(ak[s], bk, ckk); cqk = MFMA16(aq[s], bk, cqk); }
;                 const int j = 16 * tj + r; const float Gj = sG[j]; const int jpos = (j & 32) + perm32s(j & 31);
;                 f32x4 lv;
; #pragma unroll
;                 for (int e = 0; e < 4; ++e) { const int i = 16 * lw + 4 * q + e; const float Gi = sG[i], bi = sB[i];
;                     const float dec = (i >= j) ? __expf(Gi - Gj) : 0.f;
;                     lv[e] = (i > j) ? ckk[e] * bi * dec : 0.f;
;                     aqkp[i * 64 + jpos] = f2bf((i >= j) ? cqk[e] * dec : 0.f); }
;                 *(PG8_LAS f32x4*)(sL + j * 64 + 16 * lw + 4 * q) = lv;
.LBB0_271:
	s_or_b64 exec, exec, vcc
	v_readlane_b32 s40, v252, 29
	v_mul_f32_e32 v64, v65, v77
	v_readlane_b32 s41, v252, 30
	s_nop 1
	v_cndmask_b32_e64 v64, v64, 0, s[40:41]
	v_cvt_pk_bf16_f32 v64, v64, v64
	v_mov_b32_e32 v65, v121
	global_store_short v213, v64, s[26:27]
	s_and_saveexec_b64 vcc, s[48:49]
	s_cbranch_execz .LBB0_273
	v_mov_b32_e32 v64, v111
	s_waitcnt lgkmcnt(0)
	v_sub_f32_e32 v64, v64, v74
	v_mul_f32_e32 v64, 0x3fb8aa3b, v64
	v_exp_f32_e32 v76, v64
.LBB0_273:
	s_or_b64 exec, exec, vcc
	v_mul_f32_e32 v64, v66, v76
	v_cndmask_b32_e64 v64, v64, 0, s[46:47]
	v_cvt_pk_bf16_f32 v64, v64, v64
	v_mov_b32_e32 v66, v123
	v_mov_b32_e32 v72, 0
	global_store_short v214, v64, s[26:27]
	v_mov_b32_e32 v64, 0
	s_and_saveexec_b64 vcc, s[54:55]
	s_cbranch_execz .LBB0_275
	v_mov_b32_e32 v64, v113
	s_waitcnt lgkmcnt(0)
	v_sub_f32_e32 v64, v64, v74
	v_mul_f32_e32 v64, 0x3fb8aa3b, v64
	v_exp_f32_e32 v64, v64
.LBB0_275:
	s_or_b64 exec, exec, vcc
	s_waitcnt lgkmcnt(1)
	v_mul_f32_e32 v65, v70, v65
	v_mul_f32_e32 v65, v65, v76
	v_cndmask_b32_e64 v70, 0, v65, s[50:51]
	s_waitcnt lgkmcnt(0)
	v_mul_f32_e32 v65, v71, v66
	v_mul_f32_e32 v65, v65, v64
	v_mul_f32_e32 v64, v67, v64
	s_mov_b32 s14, 0x8000
	v_cndmask_b32_e64 v64, v64, 0, s[52:53]
	v_add_co_u32_e32 v78, vcc, s14, v126
	v_cvt_pk_bf16_f32 v64, v64, v64
	global_store_short v215, v64, s[26:27]
	s_nop 0
	v_addc_co_u32_e32 v79, vcc, 0, v127, vcc
	s_mov_b64 s[100:101], 0x4000
	v_lshl_add_u64 v[250:251], v[78:79], 0, s[100:101]
	v_cndmask_b32_e64 v71, 0, v65, s[56:57]
	ds_read_b128 v[64:67], v254 offset:8192
	v_mul_f32_e32 v69, v69, v75
	v_mul_f32_e32 v69, v69, v77
	ds_read_b128 v[74:77], v254 offset:9216
	ds_read_b128 v[234:237], v254 offset:10240
	ds_read_b128 v[238:241], v254 offset:11264
	ds_read_b128 v[242:245], v254 offset:12288
	ds_read_b128 v[246:249], v254 offset:13312
	v_mul_f32_e32 v68, v68, v73
	v_readlane_b32 s40, v252, 27
	v_mul_f32_e32 v68, v68, v80
	v_readlane_b32 s41, v252, 28
	v_cndmask_b32_e64 v69, v69, 0, s[36:37]
	s_nop 0
	v_cndmask_b32_e64 v68, 0, v68, s[40:41]
	ds_write_b128 v216, v[68:71] offset:1024
	s_waitcnt lgkmcnt(0)
	v_mfma_f32_16x16x32_bf16 v[68:71], v[56:59], v[64:67], 0
	v_mfma_f32_16x16x32_bf16 v[64:67], v[60:63], v[64:67], 0
	v_mfma_f32_16x16x32_bf16 v[68:71], v[48:51], v[74:77], v[68:71]
	v_mfma_f32_16x16x32_bf16 v[64:67], v[52:55], v[74:77], v[64:67]
	v_mfma_f32_16x16x32_bf16 v[68:71], v[40:43], v[234:237], v[68:71]
	v_mfma_f32_16x16x32_bf16 v[64:67], v[44:47], v[234:237], v[64:67]
	v_mfma_f32_16x16x32_bf16 v[68:71], v[32:35], v[238:241], v[68:71]
	v_mfma_f32_16x16x32_bf16 v[64:67], v[36:39], v[238:241], v[64:67]
	ds_read_b128 v[234:237], v254 offset:14336
	ds_read_b128 v[238:241], v254 offset:15360
	ds_read_b32 v74, v137 offset:128
	v_mov_b32_e32 v73, v117
	s_and_saveexec_b64 vcc, s[60:61]
	s_cbranch_execz .LBB0_277
	v_mov_b32_e32 v72, v107
	s_waitcnt lgkmcnt(0)
	v_sub_f32_e32 v72, v72, v74
	v_mul_f32_e32 v72, 0x3fb8aa3b, v72
	v_exp_f32_e32 v72, v72
.LBB0_277:
	s_or_b64 exec, exec, vcc
	s_nop 2
	v_mul_f32_e32 v64, v64, v72
	v_cndmask_b32_e64 v64, v64, 0, s[58:59]
	v_cvt_pk_bf16_f32 v64, v64, v64
	v_mov_b32_e32 v75, v119
	v_mov_b32_e32 v76, 0
	v_mov_b32_e32 v77, 0
	global_store_short v217, v64, s[26:27]
	s_and_saveexec_b64 vcc, s[68:69]
	s_cbranch_execz .LBB0_279
	v_mov_b32_e32 v64, v109
	s_waitcnt lgkmcnt(0)
	v_sub_f32_e32 v64, v64, v74
	v_mul_f32_e32 v64, 0x3fb8aa3b, v64
	v_exp_f32_e32 v77, v64
; #define PG8_LAS __attribute__((address_space(3)))
; #define MFMA16(a, b, c) __builtin_amdgcn_mfma_f32_16x16x32_bf16((a), (b), (c), 0, 0, 0)
; __device__ __forceinline__ bf16_t f2bf(float x) { return (bf16_t)(pk2(x, x) & 0xffffu); }
; __device__ __forceinline__ void phase_prep(const Args& a, PG8_LAS unsigned char* lds) {
;     ...
;         {
; #pragma unroll
;             for (int tj = 0; tj < 4; ++tj) {
;                 f32x4 ckk = {0.f, 0.f, 0.f, 0.f}, cqk = {0.f, 0.f, 0.f, 0.f};
; #pragma unroll
;                 for (int s = 0; s < 4; ++s) { const bf16x8 bk = (tj < 2) ? bkf[tj & 1][s] : *(const bf16x8*)(kbase + (size_t)(16 * tj + r) * 512 + 32 * s + 8 * q); ckk = MFMA16(ak[s], bk, ckk); cqk = MFMA16(aq[s], bk, cqk); }
;                 const int j = 16 * tj + r; const float Gj = sG[j]; const int jpos = (j & 32) + perm32s(j & 31);
;                 f32x4 lv;
; #pragma unroll
;                 for (int e = 0; e < 4; ++e) { const int i = 16 * lw + 4 * q + e; const float Gi = sG[i], bi = sB[i];
;                     const float dec = (i >= j) ? __expf(Gi - Gj) : 0.f;
;                     lv[e] = (i > j) ? ckk[e] * bi * dec : 0.f;
;                     aqkp[i * 64 + jpos] = f2bf((i >= j) ? cqk[e] * dec : 0.f); }
;                 *(PG8_LAS f32x4*)(sL + j * 64 + 16 * lw + 4 * q) = lv;
.LBB0_279:
	s_or_b64 exec, exec, vcc
	v_mul_f32_e32 v64, v65, v77
	v_cndmask_b32_e64 v64, v64, 0, s[66:67]
	v_cvt_pk_bf16_f32 v64, v64, v64
	v_mov_b32_e32 v78, v121
	global_store_short v218, v64, s[26:27]
	s_and_saveexec_b64 vcc, s[72:73]
	s_cbranch_execz .LBB0_281
	v_mov_b32_e32 v64, v111
	s_waitcnt lgkmcnt(0)
	v_sub_f32_e32 v64, v64, v74
	v_mul_f32_e32 v64, 0x3fb8aa3b, v64
	v_exp_f32_e32 v76, v64
.LBB0_281:
	s_or_b64 exec, exec, vcc
	v_mul_f32_e32 v64, v66, v76
	v_cndmask_b32_e64 v64, v64, 0, s[70:71]
	v_cvt_pk_bf16_f32 v65, v64, v64
	v_mov_b32_e32 v66, v123
	v_mov_b32_e32 v64, 0
	global_store_short v219, v65, s[26:27]
	v_mov_b32_e32 v65, 0
	s_and_saveexec_b64 vcc, s[78:79]
	s_cbranch_execz .LBB0_283
	v_mov_b32_e32 v65, v113
	s_waitcnt lgkmcnt(0)
	v_sub_f32_e32 v65, v65, v74
	v_mul_f32_e32 v65, 0x3fb8aa3b, v65
	v_exp_f32_e32 v65, v65
.LBB0_283:
	s_or_b64 exec, exec, vcc
	s_waitcnt lgkmcnt(3)
	v_mul_f32_e32 v68, v68, v73
	s_waitcnt lgkmcnt(2)
	v_mul_f32_e32 v69, v69, v75
	s_waitcnt lgkmcnt(1)
	v_mul_f32_e32 v70, v70, v78
	s_waitcnt lgkmcnt(0)
	v_mul_f32_e32 v66, v71, v66
	v_mul_f32_e32 v68, v68, v72
	v_mul_f32_e32 v69, v69, v77
	v_mul_f32_e32 v70, v70, v76
	v_mul_f32_e32 v66, v66, v65
	v_mul_f32_e32 v65, v67, v65
	v_cndmask_b32_e64 v68, 0, v68, s[64:65]
	v_cndmask_b32_e64 v69, v69, 0, s[58:59]
	v_cndmask_b32_e64 v70, 0, v70, s[42:43]
	v_cndmask_b32_e64 v71, 0, v66, s[80:81]
	v_cndmask_b32_e64 v65, v65, 0, s[76:77]
	v_cvt_pk_bf16_f32 v65, v65, v65
	ds_write_b128 v221, v[68:71] offset:1024
	v_add_co_u32_e32 v70, vcc, s35, v126
	global_store_short v220, v65, s[26:27]
	s_nop 0
	v_addc_co_u32_e32 v71, vcc, 0, v127, vcc
	s_waitcnt lgkmcnt(0)
	v_mfma_f32_16x16x32_bf16 v[56:59], v[56:59], v[242:245], 0
	v_mfma_f32_16x16x32_bf16 v[60:63], v[60:63], v[242:245], 0
	v_mfma_f32_16x16x32_bf16 v[48:51], v[48:51], v[246:249], v[56:59]
	s_nop 3
	v_mfma_f32_16x16x32_bf16 v[52:55], v[52:55], v[246:249], v[60:63]
	v_mfma_f32_16x16x32_bf16 v[40:43], v[40:43], v[234:237], v[48:51]
	s_nop 2
	v_mfma_f32_16x16x32_bf16 v[44:47], v[44:47], v[234:237], v[52:55]
	v_mfma_f32_16x16x32_bf16 v[40:43], v[32:35], v[238:241], v[40:43]
	v_mfma_f32_16x16x32_bf16 v[32:35], v[36:39], v[238:241], v[44:47]
	ds_read_b32 v37, v137 offset:192
	v_mov_b32_e32 v36, v117
	s_and_saveexec_b64 vcc, s[84:85]
	s_cbranch_execz .LBB0_285
	v_mov_b32_e32 v38, v107
	s_waitcnt lgkmcnt(0)
	v_sub_f32_e32 v38, v38, v37
	v_mul_f32_e32 v38, 0x3fb8aa3b, v38
	v_exp_f32_e32 v64, v38
.LBB0_285:
	s_or_b64 exec, exec, vcc
	s_nop 2
	v_mul_f32_e32 v32, v32, v64
	v_cndmask_b32_e64 v32, v32, 0, s[82:83]
	v_cvt_pk_bf16_f32 v39, v32, v32
	v_mov_b32_e32 v32, v119
	v_mov_b32_e32 v38, 0
	global_store_short v222, v39, s[26:27]
	v_mov_b32_e32 v39, 0
	s_and_saveexec_b64 vcc, s[90:91]
	s_cbranch_execz .LBB0_287
	v_mov_b32_e32 v39, v109
	s_waitcnt lgkmcnt(0)
	v_sub_f32_e32 v39, v39, v37
	v_mul_f32_e32 v39, 0x3fb8aa3b, v39
	v_exp_f32_e32 v39, v39
.LBB0_287:
	s_or_b64 exec, exec, vcc
	v_mul_f32_e32 v33, v33, v39
	v_cndmask_b32_e64 v33, v33, 0, s[88:89]
	v_cvt_pk_bf16_f32 v44, v33, v33
	v_mov_b32_e32 v33, v121
	global_store_short v223, v44, s[26:27]
	s_and_saveexec_b64 vcc, s[94:95]
	s_cbranch_execz .LBB0_289
	v_mov_b32_e32 v38, v111
	s_waitcnt lgkmcnt(0)
	v_sub_f32_e32 v38, v38, v37
	v_mul_f32_e32 v38, 0x3fb8aa3b, v38
	v_exp_f32_e32 v38, v38
.LBB0_289:
	s_or_b64 exec, exec, vcc
	v_mul_f32_e32 v34, v34, v38
	v_cndmask_b32_e64 v34, v34, 0, s[92:93]
	v_cvt_pk_bf16_f32 v45, v34, v34
	v_mov_b32_e32 v34, v123
	v_mov_b32_e32 v44, 0
	global_store_short v224, v45, s[26:27]
	s_and_saveexec_b64 vcc, s[6:7]
	s_cbranch_execz .LBB0_291
	v_mov_b32_e32 v44, v113
	s_waitcnt lgkmcnt(0)
	v_sub_f32_e32 v37, v44, v37
	v_mul_f32_e32 v37, 0x3fb8aa3b, v37
	v_exp_f32_e32 v44, v37
